# last-unit epilogue stores of PP0, GATE0, PP1 keep their lines in L2 (no sc1 write-through): consumers are the producer itself or its co-XCD panel group; faster store acknowledge and L2-hit re-reads
# speedup vs baseline: 1.0055x; 1.0055x over previous
.LBB0_1219:
	v_lshl_add_u32 v144, s30, 8, v1
	v_ashrrev_i32_e32 v145, 31, v144
	v_lshl_or_b32 v142, s34, 8, v147
	v_cvt_pk_bf16_f32 v126, v126, v127
	v_cvt_pk_bf16_f32 v127, v128, v129
	v_cvt_pk_bf16_f32 v128, v122, v123
	v_lshlrev_b64 v[122:123], 11, v[144:145]
	v_ashrrev_i32_e32 v143, 31, v142
	v_lshl_add_u64 v[122:123], s[6:7], 0, v[122:123]
	v_lshl_add_u64 v[122:123], v[142:143], 1, v[122:123]
	s_andn2_b64 vcc, exec, s[4:5]
	s_mov_b64 s[30:31], -1
	v_cvt_pk_bf16_f32 v129, v124, v125
	s_cbranch_vccnz .LBB0_1221
	global_store_dwordx4 v[122:123], v[126:129], off
	s_nop 1
	s_mov_b64 s[30:31], 0

.LBB0_1223:
	v_cvt_pk_bf16_f32 v118, v118, v119
	v_cvt_pk_bf16_f32 v119, v120, v121
	v_cvt_pk_bf16_f32 v120, v114, v115
	v_lshl_add_u64 v[114:115], v[122:123], 0, s[12:13]
	s_mov_b64 s[30:31], -1
	s_and_b64 vcc, exec, s[4:5]
	v_cvt_pk_bf16_f32 v121, v116, v117
	s_cbranch_vccz .LBB0_1225
	global_store_dwordx4 v[114:115], v[118:121], off
	s_nop 1
	s_mov_b64 s[30:31], 0

.LBB0_1227:
	v_or_b32_e32 v114, 16, v144
	v_ashrrev_i32_e32 v115, 31, v114
	v_cvt_pk_bf16_f32 v110, v110, v111
	v_cvt_pk_bf16_f32 v111, v112, v113
	v_cvt_pk_bf16_f32 v112, v106, v107
	v_lshlrev_b64 v[106:107], 11, v[114:115]
	v_lshl_add_u64 v[106:107], s[6:7], 0, v[106:107]
	v_lshl_add_u64 v[106:107], v[142:143], 1, v[106:107]
	s_mov_b64 s[30:31], -1
	s_and_b64 vcc, exec, s[4:5]
	v_cvt_pk_bf16_f32 v113, v108, v109
	s_cbranch_vccz .LBB0_1229
	global_store_dwordx4 v[106:107], v[110:113], off
	s_nop 1
	s_mov_b64 s[30:31], 0

.LBB0_1231:
	v_cvt_pk_bf16_f32 v102, v102, v103
	v_cvt_pk_bf16_f32 v103, v104, v105
	v_cvt_pk_bf16_f32 v104, v98, v99
	v_lshl_add_u64 v[98:99], v[106:107], 0, s[12:13]
	s_mov_b64 s[30:31], -1
	s_and_b64 vcc, exec, s[4:5]
	v_cvt_pk_bf16_f32 v105, v100, v101
	s_cbranch_vccz .LBB0_1233
	global_store_dwordx4 v[98:99], v[102:105], off
	s_nop 1
	s_mov_b64 s[30:31], 0

.LBB0_1235:
	v_or_b32_e32 v98, 32, v144
	v_ashrrev_i32_e32 v99, 31, v98
	v_cvt_pk_bf16_f32 v94, v94, v95
	v_cvt_pk_bf16_f32 v95, v96, v97
	v_cvt_pk_bf16_f32 v96, v90, v91
	v_lshlrev_b64 v[90:91], 11, v[98:99]
	v_lshl_add_u64 v[90:91], s[6:7], 0, v[90:91]
	v_lshl_add_u64 v[90:91], v[142:143], 1, v[90:91]
	s_mov_b64 s[30:31], -1
	s_and_b64 vcc, exec, s[4:5]
	v_cvt_pk_bf16_f32 v97, v92, v93
	s_cbranch_vccz .LBB0_1237
	global_store_dwordx4 v[90:91], v[94:97], off
	s_nop 1
	s_mov_b64 s[30:31], 0

.LBB0_1239:
	v_cvt_pk_bf16_f32 v86, v86, v87
	v_cvt_pk_bf16_f32 v87, v88, v89
	v_cvt_pk_bf16_f32 v88, v82, v83
	v_lshl_add_u64 v[82:83], v[90:91], 0, s[12:13]
	s_mov_b64 s[30:31], -1
	s_and_b64 vcc, exec, s[4:5]
	v_cvt_pk_bf16_f32 v89, v84, v85
	s_cbranch_vccz .LBB0_1241
	global_store_dwordx4 v[82:83], v[86:89], off
	s_nop 1
	s_mov_b64 s[30:31], 0

.LBB0_1243:
	v_or_b32_e32 v82, 48, v144
	v_ashrrev_i32_e32 v83, 31, v82
	v_cvt_pk_bf16_f32 v78, v78, v79
	v_cvt_pk_bf16_f32 v79, v80, v81
	v_cvt_pk_bf16_f32 v80, v74, v75
	v_lshlrev_b64 v[74:75], 11, v[82:83]
	v_lshl_add_u64 v[74:75], s[6:7], 0, v[74:75]
	v_lshl_add_u64 v[74:75], v[142:143], 1, v[74:75]
	s_mov_b64 s[30:31], -1
	s_and_b64 vcc, exec, s[4:5]
	v_cvt_pk_bf16_f32 v81, v76, v77
	s_cbranch_vccz .LBB0_1245
	global_store_dwordx4 v[74:75], v[78:81], off
	s_nop 1
	s_mov_b64 s[30:31], 0

.LBB0_1247:
	v_cvt_pk_bf16_f32 v70, v70, v71
	v_cvt_pk_bf16_f32 v71, v72, v73
	v_cvt_pk_bf16_f32 v72, v66, v67
	v_lshl_add_u64 v[66:67], v[74:75], 0, s[12:13]
	s_mov_b64 s[30:31], -1
	s_and_b64 vcc, exec, s[4:5]
	v_cvt_pk_bf16_f32 v73, v68, v69
	s_cbranch_vccz .LBB0_1249
	global_store_dwordx4 v[66:67], v[70:73], off
	s_nop 1
	s_mov_b64 s[30:31], 0

.LBB0_1251:
	v_lshlrev_b64 v[66:67], 11, v[144:145]
	v_cvt_pk_bf16_f32 v62, v62, v63
	v_cvt_pk_bf16_f32 v63, v64, v65
	v_cvt_pk_bf16_f32 v64, v58, v59
	v_lshl_add_u64 v[58:59], s[6:7], 0, v[66:67]
	v_lshl_add_u64 v[58:59], v[142:143], 1, v[58:59]
	v_lshl_add_u64 v[58:59], v[58:59], 0, s[14:15]
	s_mov_b64 s[30:31], -1
	s_and_b64 vcc, exec, s[4:5]
	v_cvt_pk_bf16_f32 v65, v60, v61
	s_cbranch_vccz .LBB0_1253
	global_store_dwordx4 v[58:59], v[62:65], off
	s_nop 1
	s_mov_b64 s[30:31], 0

.LBB0_1255:
	v_cvt_pk_bf16_f32 v54, v54, v55
	v_cvt_pk_bf16_f32 v55, v56, v57
	v_cvt_pk_bf16_f32 v56, v50, v51
	v_lshl_add_u64 v[50:51], v[58:59], 0, s[12:13]
	s_mov_b64 s[30:31], -1
	s_and_b64 vcc, exec, s[4:5]
	v_cvt_pk_bf16_f32 v57, v52, v53
	s_cbranch_vccz .LBB0_1257
	global_store_dwordx4 v[50:51], v[54:57], off
	s_nop 1
	s_mov_b64 s[30:31], 0

.LBB0_1259:
	v_lshlrev_b64 v[50:51], 11, v[144:145]
	v_cvt_pk_bf16_f32 v46, v46, v47
	v_cvt_pk_bf16_f32 v47, v48, v49
	v_cvt_pk_bf16_f32 v48, v42, v43
	v_lshl_add_u64 v[42:43], s[6:7], 0, v[50:51]
	v_lshl_add_u64 v[42:43], v[142:143], 1, v[42:43]
	v_lshl_add_u64 v[42:43], v[42:43], 0, s[16:17]
	s_mov_b64 s[30:31], -1
	s_and_b64 vcc, exec, s[4:5]
	v_cvt_pk_bf16_f32 v49, v44, v45
	s_cbranch_vccz .LBB0_1261
	global_store_dwordx4 v[42:43], v[46:49], off
	s_nop 1
	s_mov_b64 s[30:31], 0

.LBB0_1263:
	v_cvt_pk_bf16_f32 v38, v38, v39
	v_cvt_pk_bf16_f32 v39, v40, v41
	v_cvt_pk_bf16_f32 v40, v34, v35
	v_lshl_add_u64 v[34:35], v[42:43], 0, s[12:13]
	s_mov_b64 s[30:31], -1
	s_and_b64 vcc, exec, s[4:5]
	v_cvt_pk_bf16_f32 v41, v36, v37
	s_cbranch_vccz .LBB0_1265
	global_store_dwordx4 v[34:35], v[38:41], off
	s_nop 1
	s_mov_b64 s[30:31], 0

.LBB0_1267:
	v_lshlrev_b64 v[34:35], 11, v[144:145]
	v_cvt_pk_bf16_f32 v30, v30, v31
	v_cvt_pk_bf16_f32 v31, v32, v33
	v_cvt_pk_bf16_f32 v32, v26, v27
	v_lshl_add_u64 v[26:27], s[6:7], 0, v[34:35]
	v_lshl_add_u64 v[26:27], v[142:143], 1, v[26:27]
	v_lshl_add_u64 v[26:27], v[26:27], 0, s[18:19]
	s_mov_b64 s[30:31], -1
	s_and_b64 vcc, exec, s[4:5]
	v_cvt_pk_bf16_f32 v33, v28, v29
	s_cbranch_vccz .LBB0_1269
	global_store_dwordx4 v[26:27], v[30:33], off
	s_nop 1
	s_mov_b64 s[30:31], 0

.LBB0_1271:
	v_cvt_pk_bf16_f32 v22, v22, v23
	v_cvt_pk_bf16_f32 v23, v24, v25
	v_cvt_pk_bf16_f32 v24, v18, v19
	v_lshl_add_u64 v[18:19], v[26:27], 0, s[12:13]
	s_mov_b64 s[30:31], -1
	s_and_b64 vcc, exec, s[4:5]
	v_cvt_pk_bf16_f32 v25, v20, v21
	s_cbranch_vccz .LBB0_1273
	global_store_dwordx4 v[18:19], v[22:25], off
	s_nop 1
	s_mov_b64 s[30:31], 0

.LBB0_1275:
	v_lshlrev_b64 v[18:19], 11, v[144:145]
	v_cvt_pk_bf16_f32 v14, v14, v15
	v_cvt_pk_bf16_f32 v15, v16, v17
	v_cvt_pk_bf16_f32 v16, v10, v11
	v_lshl_add_u64 v[10:11], s[6:7], 0, v[18:19]
	v_lshl_add_u64 v[10:11], v[142:143], 1, v[10:11]
	v_lshl_add_u64 v[10:11], v[10:11], 0, s[20:21]
	s_mov_b64 s[30:31], -1
	s_and_b64 vcc, exec, s[4:5]
	v_cvt_pk_bf16_f32 v17, v12, v13
	s_cbranch_vccz .LBB0_1277
	global_store_dwordx4 v[10:11], v[14:17], off
	s_nop 1
	s_mov_b64 s[30:31], 0

.LBB0_1279:
	v_cvt_pk_bf16_f32 v6, v6, v7
	v_cvt_pk_bf16_f32 v7, v8, v9
	v_cvt_pk_bf16_f32 v8, v2, v3
	v_lshl_add_u64 v[2:3], v[10:11], 0, s[12:13]
	s_mov_b64 s[30:31], -1
	s_and_b64 vcc, exec, s[4:5]
	v_cvt_pk_bf16_f32 v9, v4, v5
	s_cbranch_vccz .LBB0_1282
	global_store_dwordx4 v[2:3], v[6:9], off
	s_nop 1
	s_cbranch_execz .LBB0_1283

.LBB0_1311:
	v_lshl_add_u32 v174, s34, 8, v181
	v_lshl_or_b32 v172, s10, 8, v183
	v_ashrrev_i32_e32 v175, 31, v174
	v_lshlrev_b64 v[130:131], 10, v[174:175]
	v_ashrrev_i32_e32 v173, 31, v172
	v_lshl_add_u64 v[130:131], v[130:131], 0, v[172:173]
	v_lshlrev_b64 v[130:131], 1, v[130:131]
	v_lshl_add_u64 v[132:133], s[0:1], 0, v[130:131]
	v_or_b32_e32 v176, 16, v174
	v_lshl_add_u64 v[134:135], s[12:13], 0, v[130:131]
	flat_load_dwordx4 v[198:201], v[132:133]
	flat_load_dwordx4 v[202:205], v[134:135]
	v_ashrrev_i32_e32 v177, 31, v176
	v_lshlrev_b64 v[132:133], 10, v[176:177]
	v_lshl_add_u64 v[132:133], v[132:133], 0, v[172:173]
	v_or_b32_e32 v130, 0x100, v130
	v_lshlrev_b64 v[132:133], 1, v[132:133]
	v_lshl_add_u64 v[134:135], s[0:1], 0, v[130:131]
	v_lshl_add_u64 v[142:143], s[12:13], 0, v[132:133]
	v_lshl_add_u64 v[130:131], s[12:13], 0, v[130:131]
	v_lshl_add_u64 v[136:137], s[0:1], 0, v[132:133]
	v_or_b32_e32 v132, 0x100, v132
	flat_load_dwordx4 v[146:149], v[134:135]
	flat_load_dwordx4 v[150:153], v[130:131]
	flat_load_dwordx4 v[138:141], v[136:137]
	s_nop 0
	flat_load_dwordx4 v[142:145], v[142:143]
	v_lshl_add_u64 v[130:131], s[0:1], 0, v[132:133]
	v_lshl_add_u64 v[134:135], s[12:13], 0, v[132:133]
	flat_load_dwordx4 v[130:133], v[130:131]
	s_nop 0
	flat_load_dwordx4 v[134:137], v[134:135]
	v_mul_f32_e32 v122, v194, v122
	v_mul_f32_e32 v122, 0xbfb8aa3b, v122
	v_exp_f32_e32 v122, v122
	v_mul_f32_e32 v126, v194, v126
	v_mul_f32_e32 v127, v194, v127
	v_mul_f32_e32 v123, v194, v123
	v_mul_f32_e32 v126, 0xbfb8aa3b, v126
	v_mul_f32_e32 v127, 0xbfb8aa3b, v127
	v_mul_f32_e32 v128, v194, v128
	v_mul_f32_e32 v129, v194, v129
	v_mul_f32_e32 v124, v194, v124
	v_mul_f32_e32 v125, v194, v125
	v_mul_f32_e32 v123, 0xbfb8aa3b, v123
	v_exp_f32_e32 v126, v126
	v_exp_f32_e32 v127, v127
	v_mul_f32_e32 v128, 0xbfb8aa3b, v128
	v_mul_f32_e32 v129, 0xbfb8aa3b, v129
	v_mul_f32_e32 v124, 0xbfb8aa3b, v124
	v_mul_f32_e32 v125, 0xbfb8aa3b, v125
	v_exp_f32_e32 v123, v123
	v_add_f32_e32 v122, 1.0, v122
	v_exp_f32_e32 v128, v128
	v_exp_f32_e32 v129, v129
	v_exp_f32_e32 v124, v124
	v_exp_f32_e32 v125, v125
	v_rcp_f32_e32 v122, v122
	v_add_f32_e32 v126, 1.0, v126
	v_add_f32_e32 v127, 1.0, v127
	v_add_f32_e32 v123, 1.0, v123
	v_rcp_f32_e32 v126, v126
	v_rcp_f32_e32 v127, v127
	v_add_f32_e32 v128, 1.0, v128
	v_add_f32_e32 v129, 1.0, v129
	v_add_f32_e32 v124, 1.0, v124
	v_rcp_f32_e32 v123, v123
	v_rcp_f32_e32 v206, v128
	v_rcp_f32_e32 v207, v129
	v_rcp_f32_e32 v124, v124
	s_andn2_b64 vcc, exec, s[6:7]
	s_mov_b64 s[34:35], -1
	s_waitcnt vmcnt(0) lgkmcnt(0)
	v_lshlrev_b32_e32 v195, 16, v200
	v_lshlrev_b32_e32 v210, 16, v204
	v_fmac_f32_e32 v195, v122, v210
	v_add_f32_e32 v122, 1.0, v125
	v_rcp_f32_e32 v122, v122
	v_lshlrev_b32_e32 v128, 16, v198
	v_lshlrev_b32_e32 v208, 16, v202
	v_and_b32_e32 v197, 0xffff0000, v198
	v_and_b32_e32 v202, 0xffff0000, v202
	v_lshlrev_b32_e32 v129, 16, v199
	v_and_b32_e32 v198, 0xffff0000, v199
	v_and_b32_e32 v199, 0xffff0000, v200
	v_and_b32_e32 v200, 0xffff0000, v204
	v_fmac_f32_e32 v128, v126, v208
	v_fmac_f32_e32 v197, v127, v202
	v_lshlrev_b64 v[126:127], 11, v[174:175]
	v_lshlrev_b32_e32 v209, 16, v203
	v_and_b32_e32 v203, 0xffff0000, v203
	v_lshlrev_b32_e32 v196, 16, v201
	v_lshlrev_b32_e32 v204, 16, v205
	v_fmac_f32_e32 v199, v123, v200
	v_and_b32_e32 v200, 0xffff0000, v201
	v_and_b32_e32 v123, 0xffff0000, v205
	v_lshl_add_u64 v[126:127], s[14:15], 0, v[126:127]
	v_fmac_f32_e32 v129, v206, v209
	v_fmac_f32_e32 v198, v207, v203
	v_fmac_f32_e32 v196, v124, v204
	v_fmac_f32_e32 v200, v122, v123
	v_lshl_add_u64 v[126:127], v[172:173], 1, v[126:127]
	v_cvt_pk_bf16_f32 v122, v128, v197
	v_cvt_pk_bf16_f32 v123, v129, v198
	v_cvt_pk_bf16_f32 v124, v195, v199
	v_cvt_pk_bf16_f32 v125, v196, v200
	s_cbranch_vccnz .LBB0_1313
	global_store_dwordx4 v[126:127], v[122:125], off
	s_nop 1
	s_mov_b64 s[34:35], 0

.LBB0_1315:
	v_mul_f32_e32 v118, v194, v118
	v_mul_f32_e32 v118, 0xbfb8aa3b, v118
	v_mul_f32_e32 v119, v194, v119
	v_exp_f32_e32 v118, v118
	v_mul_f32_e32 v119, 0xbfb8aa3b, v119
	v_exp_f32_e32 v119, v119
	v_lshlrev_b32_e32 v122, 16, v146
	v_add_f32_e32 v118, 1.0, v118
	v_rcp_f32_e32 v118, v118
	v_add_f32_e32 v119, 1.0, v119
	v_rcp_f32_e32 v119, v119
	v_lshlrev_b32_e32 v123, 16, v150
	v_fmac_f32_e32 v122, v118, v123
	v_and_b32_e32 v124, 0xffff0000, v146
	v_and_b32_e32 v118, 0xffff0000, v150
	v_fmac_f32_e32 v124, v119, v118
	v_mul_f32_e32 v118, v194, v120
	v_mul_f32_e32 v118, 0xbfb8aa3b, v118
	v_mul_f32_e32 v119, v194, v121
	v_exp_f32_e32 v118, v118
	v_mul_f32_e32 v119, 0xbfb8aa3b, v119
	v_mul_f32_e32 v114, v194, v114
	v_exp_f32_e32 v119, v119
	v_mul_f32_e32 v114, 0xbfb8aa3b, v114
	v_mul_f32_e32 v115, v194, v115
	v_exp_f32_e32 v114, v114
	v_mul_f32_e32 v115, 0xbfb8aa3b, v115
	v_exp_f32_e32 v115, v115
	v_add_f32_e32 v118, 1.0, v118
	v_rcp_f32_e32 v118, v118
	v_add_f32_e32 v119, 1.0, v119
	v_rcp_f32_e32 v119, v119
	v_add_f32_e32 v114, 1.0, v114
	v_rcp_f32_e32 v114, v114
	v_add_f32_e32 v115, 1.0, v115
	v_lshlrev_b32_e32 v123, 16, v147
	v_lshlrev_b32_e32 v120, 16, v151
	v_rcp_f32_e32 v115, v115
	v_fmac_f32_e32 v123, v118, v120
	v_and_b32_e32 v121, 0xffff0000, v147
	v_and_b32_e32 v118, 0xffff0000, v151
	v_fmac_f32_e32 v121, v119, v118
	v_lshlrev_b32_e32 v120, 16, v148
	v_lshlrev_b32_e32 v118, 16, v152
	v_fmac_f32_e32 v120, v114, v118
	v_and_b32_e32 v146, 0xffff0000, v148
	v_and_b32_e32 v114, 0xffff0000, v152
	v_fmac_f32_e32 v146, v115, v114
	v_mul_f32_e32 v114, v194, v116
	v_mul_f32_e32 v114, 0xbfb8aa3b, v114
	v_mul_f32_e32 v115, v194, v117
	v_exp_f32_e32 v114, v114
	v_mul_f32_e32 v115, 0xbfb8aa3b, v115
	v_exp_f32_e32 v115, v115
	v_lshlrev_b32_e32 v125, 16, v149
	v_add_f32_e32 v114, 1.0, v114
	v_rcp_f32_e32 v114, v114
	v_add_f32_e32 v115, 1.0, v115
	v_rcp_f32_e32 v115, v115
	v_lshlrev_b32_e32 v116, 16, v153
	v_fmac_f32_e32 v125, v114, v116
	v_and_b32_e32 v147, 0xffff0000, v149
	v_and_b32_e32 v114, 0xffff0000, v153
	v_fmac_f32_e32 v147, v115, v114
	v_lshl_add_u64 v[118:119], v[126:127], 0, s[22:23]
	s_mov_b64 s[34:35], -1
	s_and_b64 vcc, exec, s[6:7]
	v_cvt_pk_bf16_f32 v114, v122, v124
	v_cvt_pk_bf16_f32 v115, v123, v121
	v_cvt_pk_bf16_f32 v116, v120, v146
	v_cvt_pk_bf16_f32 v117, v125, v147
	s_cbranch_vccz .LBB0_1317
	global_store_dwordx4 v[118:119], v[114:117], off
	s_nop 1
	s_mov_b64 s[34:35], 0

.LBB0_1321:
	s_or_b64 exec, exec, s[36:37]
	v_or_b32_e32 v146, 32, v174
	v_ashrrev_i32_e32 v147, 31, v146
	s_waitcnt lgkmcnt(0)
	v_lshlrev_b64 v[114:115], 10, v[146:147]
	v_lshl_add_u64 v[114:115], v[114:115], 0, v[172:173]
	v_lshlrev_b64 v[114:115], 1, v[114:115]
	v_lshl_add_u64 v[116:117], s[0:1], 0, v[114:115]
	v_lshl_add_u64 v[118:119], s[12:13], 0, v[114:115]
	v_or_b32_e32 v114, 0x100, v114
	flat_load_dwordx4 v[122:125], v[116:117]
	flat_load_dwordx4 v[126:129], v[118:119]
	v_lshl_add_u64 v[116:117], s[0:1], 0, v[114:115]
	v_lshl_add_u64 v[118:119], s[12:13], 0, v[114:115]
	flat_load_dwordx4 v[114:117], v[116:117]
	s_nop 0
	flat_load_dwordx4 v[118:121], v[118:119]
	v_mul_f32_e32 v110, v193, v110
	v_mul_f32_e32 v110, 0xbfb8aa3b, v110
	v_mul_f32_e32 v111, v193, v111
	v_exp_f32_e32 v110, v110
	v_mul_f32_e32 v111, 0xbfb8aa3b, v111
	v_exp_f32_e32 v111, v111
	v_lshlrev_b32_e32 v148, 16, v138
	v_add_f32_e32 v110, 1.0, v110
	v_rcp_f32_e32 v110, v110
	v_add_f32_e32 v111, 1.0, v111
	v_rcp_f32_e32 v111, v111
	v_lshlrev_b32_e32 v149, 16, v142
	v_fmac_f32_e32 v148, v110, v149
	v_and_b32_e32 v149, 0xffff0000, v138
	v_and_b32_e32 v110, 0xffff0000, v142
	v_fmac_f32_e32 v149, v111, v110
	v_mul_f32_e32 v110, v193, v112
	v_mul_f32_e32 v110, 0xbfb8aa3b, v110
	v_mul_f32_e32 v111, v193, v113
	v_exp_f32_e32 v110, v110
	v_mul_f32_e32 v111, 0xbfb8aa3b, v111
	v_mul_f32_e32 v106, v193, v106
	v_exp_f32_e32 v111, v111
	v_mul_f32_e32 v106, 0xbfb8aa3b, v106
	v_mul_f32_e32 v107, v193, v107
	v_exp_f32_e32 v106, v106
	v_mul_f32_e32 v107, 0xbfb8aa3b, v107
	v_exp_f32_e32 v107, v107
	v_add_f32_e32 v110, 1.0, v110
	v_rcp_f32_e32 v110, v110
	v_add_f32_e32 v111, 1.0, v111
	v_rcp_f32_e32 v111, v111
	v_add_f32_e32 v106, 1.0, v106
	v_rcp_f32_e32 v106, v106
	v_add_f32_e32 v107, 1.0, v107
	v_lshlrev_b32_e32 v138, 16, v139
	v_lshlrev_b32_e32 v112, 16, v143
	v_rcp_f32_e32 v107, v107
	v_fmac_f32_e32 v138, v110, v112
	v_and_b32_e32 v113, 0xffff0000, v139
	v_and_b32_e32 v110, 0xffff0000, v143
	v_fmac_f32_e32 v113, v111, v110
	v_lshlrev_b32_e32 v112, 16, v140
	v_lshlrev_b32_e32 v110, 16, v144
	v_fmac_f32_e32 v112, v106, v110
	v_and_b32_e32 v140, 0xffff0000, v140
	v_and_b32_e32 v106, 0xffff0000, v144
	v_fmac_f32_e32 v140, v107, v106
	v_mul_f32_e32 v106, v193, v108
	v_mul_f32_e32 v106, 0xbfb8aa3b, v106
	v_mul_f32_e32 v107, v193, v109
	v_exp_f32_e32 v106, v106
	v_mul_f32_e32 v107, 0xbfb8aa3b, v107
	v_exp_f32_e32 v107, v107
	v_lshlrev_b32_e32 v139, 16, v141
	v_add_f32_e32 v106, 1.0, v106
	v_rcp_f32_e32 v106, v106
	v_add_f32_e32 v107, 1.0, v107
	v_rcp_f32_e32 v107, v107
	v_lshlrev_b32_e32 v108, 16, v145
	v_lshlrev_b64 v[110:111], 11, v[176:177]
	v_fmac_f32_e32 v139, v106, v108
	v_and_b32_e32 v141, 0xffff0000, v141
	v_and_b32_e32 v106, 0xffff0000, v145
	v_lshl_add_u64 v[110:111], s[14:15], 0, v[110:111]
	v_fmac_f32_e32 v141, v107, v106
	v_lshl_add_u64 v[110:111], v[172:173], 1, v[110:111]
	s_mov_b64 s[36:37], -1
	s_and_b64 vcc, exec, s[6:7]
	v_cvt_pk_bf16_f32 v106, v148, v149
	v_cvt_pk_bf16_f32 v107, v138, v113
	v_cvt_pk_bf16_f32 v108, v112, v140
	v_cvt_pk_bf16_f32 v109, v139, v141
	s_cbranch_vccz .LBB0_1323
	global_store_dwordx4 v[110:111], v[106:109], off
	s_nop 1
	s_mov_b64 s[36:37], 0

.LBB0_1325:
	v_mul_f32_e32 v102, v193, v102
	v_mul_f32_e32 v102, 0xbfb8aa3b, v102
	v_mul_f32_e32 v103, v193, v103
	v_exp_f32_e32 v102, v102
	v_mul_f32_e32 v103, 0xbfb8aa3b, v103
	v_exp_f32_e32 v103, v103
	v_lshlrev_b32_e32 v106, 16, v130
	v_add_f32_e32 v102, 1.0, v102
	v_rcp_f32_e32 v102, v102
	v_add_f32_e32 v103, 1.0, v103
	v_rcp_f32_e32 v103, v103
	v_lshlrev_b32_e32 v107, 16, v134
	v_fmac_f32_e32 v106, v102, v107
	v_and_b32_e32 v108, 0xffff0000, v130
	v_and_b32_e32 v102, 0xffff0000, v134
	v_fmac_f32_e32 v108, v103, v102
	v_mul_f32_e32 v102, v193, v104
	v_mul_f32_e32 v102, 0xbfb8aa3b, v102
	v_mul_f32_e32 v103, v193, v105
	v_exp_f32_e32 v102, v102
	v_mul_f32_e32 v103, 0xbfb8aa3b, v103
	v_mul_f32_e32 v98, v193, v98
	v_exp_f32_e32 v103, v103
	v_mul_f32_e32 v98, 0xbfb8aa3b, v98
	v_mul_f32_e32 v99, v193, v99
	v_exp_f32_e32 v98, v98
	v_mul_f32_e32 v99, 0xbfb8aa3b, v99
	v_exp_f32_e32 v99, v99
	v_add_f32_e32 v102, 1.0, v102
	v_rcp_f32_e32 v102, v102
	v_add_f32_e32 v103, 1.0, v103
	v_rcp_f32_e32 v103, v103
	v_add_f32_e32 v98, 1.0, v98
	v_rcp_f32_e32 v98, v98
	v_add_f32_e32 v99, 1.0, v99
	v_lshlrev_b32_e32 v107, 16, v131
	v_lshlrev_b32_e32 v104, 16, v135
	v_rcp_f32_e32 v99, v99
	v_fmac_f32_e32 v107, v102, v104
	v_and_b32_e32 v105, 0xffff0000, v131
	v_and_b32_e32 v102, 0xffff0000, v135
	v_fmac_f32_e32 v105, v103, v102
	v_lshlrev_b32_e32 v104, 16, v132
	v_lshlrev_b32_e32 v102, 16, v136
	v_fmac_f32_e32 v104, v98, v102
	v_and_b32_e32 v130, 0xffff0000, v132
	v_and_b32_e32 v98, 0xffff0000, v136
	v_fmac_f32_e32 v130, v99, v98
	v_mul_f32_e32 v98, v193, v100
	v_mul_f32_e32 v98, 0xbfb8aa3b, v98
	v_mul_f32_e32 v99, v193, v101
	v_exp_f32_e32 v98, v98
	v_mul_f32_e32 v99, 0xbfb8aa3b, v99
	v_exp_f32_e32 v99, v99
	v_lshlrev_b32_e32 v109, 16, v133
	v_add_f32_e32 v98, 1.0, v98
	v_rcp_f32_e32 v98, v98
	v_add_f32_e32 v99, 1.0, v99
	v_rcp_f32_e32 v99, v99
	v_lshlrev_b32_e32 v100, 16, v137
	v_fmac_f32_e32 v109, v98, v100
	v_and_b32_e32 v131, 0xffff0000, v133
	v_and_b32_e32 v98, 0xffff0000, v137
	v_fmac_f32_e32 v131, v99, v98
	v_lshl_add_u64 v[102:103], v[110:111], 0, s[22:23]
	s_mov_b64 s[36:37], -1
	s_and_b64 vcc, exec, s[6:7]
	v_cvt_pk_bf16_f32 v98, v106, v108
	v_cvt_pk_bf16_f32 v99, v107, v105
	v_cvt_pk_bf16_f32 v100, v104, v130
	v_cvt_pk_bf16_f32 v101, v109, v131
	s_cbranch_vccz .LBB0_1327
	global_store_dwordx4 v[102:103], v[98:101], off
	s_nop 1
	s_mov_b64 s[36:37], 0

.LBB0_1331:
	s_or_b64 exec, exec, s[36:37]
	v_or_b32_e32 v130, 48, v174
	v_ashrrev_i32_e32 v131, 31, v130
	s_waitcnt lgkmcnt(0)
	v_lshlrev_b64 v[98:99], 10, v[130:131]
	v_lshl_add_u64 v[98:99], v[98:99], 0, v[172:173]
	v_lshlrev_b64 v[98:99], 1, v[98:99]
	v_lshl_add_u64 v[100:101], s[0:1], 0, v[98:99]
	v_lshl_add_u64 v[102:103], s[12:13], 0, v[98:99]
	v_or_b32_e32 v98, 0x100, v98
	flat_load_dwordx4 v[106:109], v[100:101]
	flat_load_dwordx4 v[110:113], v[102:103]
	v_lshl_add_u64 v[100:101], s[0:1], 0, v[98:99]
	v_lshl_add_u64 v[102:103], s[12:13], 0, v[98:99]
	flat_load_dwordx4 v[98:101], v[100:101]
	s_nop 0
	flat_load_dwordx4 v[102:105], v[102:103]
	v_mul_f32_e32 v94, v192, v94
	v_mul_f32_e32 v94, 0xbfb8aa3b, v94
	v_mul_f32_e32 v95, v192, v95
	v_exp_f32_e32 v94, v94
	v_mul_f32_e32 v95, 0xbfb8aa3b, v95
	v_exp_f32_e32 v95, v95
	s_waitcnt vmcnt(0)
	v_lshlrev_b32_e32 v132, 16, v122
	v_add_f32_e32 v94, 1.0, v94
	v_rcp_f32_e32 v94, v94
	v_add_f32_e32 v95, 1.0, v95
	v_rcp_f32_e32 v95, v95
	v_lshlrev_b32_e32 v133, 16, v126
	v_fmac_f32_e32 v132, v94, v133
	v_and_b32_e32 v133, 0xffff0000, v122
	v_and_b32_e32 v94, 0xffff0000, v126
	v_fmac_f32_e32 v133, v95, v94
	v_mul_f32_e32 v94, v192, v96
	v_mul_f32_e32 v94, 0xbfb8aa3b, v94
	v_mul_f32_e32 v95, v192, v97
	v_exp_f32_e32 v94, v94
	v_mul_f32_e32 v95, 0xbfb8aa3b, v95
	v_mul_f32_e32 v90, v192, v90
	v_exp_f32_e32 v95, v95
	v_mul_f32_e32 v90, 0xbfb8aa3b, v90
	v_mul_f32_e32 v91, v192, v91
	v_exp_f32_e32 v90, v90
	v_mul_f32_e32 v91, 0xbfb8aa3b, v91
	v_exp_f32_e32 v91, v91
	v_add_f32_e32 v94, 1.0, v94
	v_rcp_f32_e32 v94, v94
	v_add_f32_e32 v95, 1.0, v95
	v_rcp_f32_e32 v95, v95
	v_add_f32_e32 v90, 1.0, v90
	v_rcp_f32_e32 v90, v90
	v_add_f32_e32 v91, 1.0, v91
	v_lshlrev_b32_e32 v122, 16, v123
	v_lshlrev_b32_e32 v96, 16, v127
	v_rcp_f32_e32 v91, v91
	v_fmac_f32_e32 v122, v94, v96
	v_and_b32_e32 v97, 0xffff0000, v123
	v_and_b32_e32 v94, 0xffff0000, v127
	v_fmac_f32_e32 v97, v95, v94
	v_lshlrev_b32_e32 v96, 16, v124
	v_lshlrev_b32_e32 v94, 16, v128
	v_fmac_f32_e32 v96, v90, v94
	v_and_b32_e32 v124, 0xffff0000, v124
	v_and_b32_e32 v90, 0xffff0000, v128
	v_fmac_f32_e32 v124, v91, v90
	v_mul_f32_e32 v90, v192, v92
	v_mul_f32_e32 v90, 0xbfb8aa3b, v90
	v_mul_f32_e32 v91, v192, v93
	v_exp_f32_e32 v90, v90
	v_mul_f32_e32 v91, 0xbfb8aa3b, v91
	v_exp_f32_e32 v91, v91
	v_lshlrev_b32_e32 v123, 16, v125
	v_add_f32_e32 v90, 1.0, v90
	v_rcp_f32_e32 v90, v90
	v_add_f32_e32 v91, 1.0, v91
	v_rcp_f32_e32 v91, v91
	v_lshlrev_b32_e32 v92, 16, v129
	v_lshlrev_b64 v[94:95], 11, v[146:147]
	v_fmac_f32_e32 v123, v90, v92
	v_and_b32_e32 v125, 0xffff0000, v125
	v_and_b32_e32 v90, 0xffff0000, v129
	v_lshl_add_u64 v[94:95], s[14:15], 0, v[94:95]
	v_fmac_f32_e32 v125, v91, v90
	v_lshl_add_u64 v[94:95], v[172:173], 1, v[94:95]
	s_mov_b64 s[36:37], -1
	s_and_b64 vcc, exec, s[6:7]
	v_cvt_pk_bf16_f32 v90, v132, v133
	v_cvt_pk_bf16_f32 v91, v122, v97
	v_cvt_pk_bf16_f32 v92, v96, v124
	v_cvt_pk_bf16_f32 v93, v123, v125
	s_cbranch_vccz .LBB0_1333
	global_store_dwordx4 v[94:95], v[90:93], off
	s_nop 1
	s_mov_b64 s[36:37], 0

.LBB0_1335:
	v_mul_f32_e32 v86, v192, v86
	v_mul_f32_e32 v86, 0xbfb8aa3b, v86
	v_mul_f32_e32 v87, v192, v87
	v_exp_f32_e32 v86, v86
	v_mul_f32_e32 v87, 0xbfb8aa3b, v87
	v_exp_f32_e32 v87, v87
	v_lshlrev_b32_e32 v90, 16, v114
	v_add_f32_e32 v86, 1.0, v86
	v_rcp_f32_e32 v86, v86
	v_add_f32_e32 v87, 1.0, v87
	v_rcp_f32_e32 v87, v87
	v_lshlrev_b32_e32 v91, 16, v118
	v_fmac_f32_e32 v90, v86, v91
	v_and_b32_e32 v92, 0xffff0000, v114
	v_and_b32_e32 v86, 0xffff0000, v118
	v_fmac_f32_e32 v92, v87, v86
	v_mul_f32_e32 v86, v192, v88
	v_mul_f32_e32 v86, 0xbfb8aa3b, v86
	v_mul_f32_e32 v87, v192, v89
	v_exp_f32_e32 v86, v86
	v_mul_f32_e32 v87, 0xbfb8aa3b, v87
	v_mul_f32_e32 v82, v192, v82
	v_exp_f32_e32 v87, v87
	v_mul_f32_e32 v82, 0xbfb8aa3b, v82
	v_mul_f32_e32 v83, v192, v83
	v_exp_f32_e32 v82, v82
	v_mul_f32_e32 v83, 0xbfb8aa3b, v83
	v_exp_f32_e32 v83, v83
	v_add_f32_e32 v86, 1.0, v86
	v_rcp_f32_e32 v86, v86
	v_add_f32_e32 v87, 1.0, v87
	v_rcp_f32_e32 v87, v87
	v_add_f32_e32 v82, 1.0, v82
	v_rcp_f32_e32 v82, v82
	v_add_f32_e32 v83, 1.0, v83
	v_lshlrev_b32_e32 v91, 16, v115
	v_lshlrev_b32_e32 v88, 16, v119
	v_rcp_f32_e32 v83, v83
	v_fmac_f32_e32 v91, v86, v88
	v_and_b32_e32 v89, 0xffff0000, v115
	v_and_b32_e32 v86, 0xffff0000, v119
	v_fmac_f32_e32 v89, v87, v86
	v_lshlrev_b32_e32 v88, 16, v116
	v_lshlrev_b32_e32 v86, 16, v120
	v_fmac_f32_e32 v88, v82, v86
	v_and_b32_e32 v114, 0xffff0000, v116
	v_and_b32_e32 v82, 0xffff0000, v120
	v_fmac_f32_e32 v114, v83, v82
	v_mul_f32_e32 v82, v192, v84
	v_mul_f32_e32 v82, 0xbfb8aa3b, v82
	v_mul_f32_e32 v83, v192, v85
	v_exp_f32_e32 v82, v82
	v_mul_f32_e32 v83, 0xbfb8aa3b, v83
	v_exp_f32_e32 v83, v83
	v_lshlrev_b32_e32 v93, 16, v117
	v_add_f32_e32 v82, 1.0, v82
	v_rcp_f32_e32 v82, v82
	v_add_f32_e32 v83, 1.0, v83
	v_rcp_f32_e32 v83, v83
	v_lshlrev_b32_e32 v84, 16, v121
	v_fmac_f32_e32 v93, v82, v84
	v_and_b32_e32 v115, 0xffff0000, v117
	v_and_b32_e32 v82, 0xffff0000, v121
	v_fmac_f32_e32 v115, v83, v82
	v_lshl_add_u64 v[86:87], v[94:95], 0, s[22:23]
	s_mov_b64 s[36:37], -1
	s_and_b64 vcc, exec, s[6:7]
	v_cvt_pk_bf16_f32 v82, v90, v92
	v_cvt_pk_bf16_f32 v83, v91, v89
	v_cvt_pk_bf16_f32 v84, v88, v114
	v_cvt_pk_bf16_f32 v85, v93, v115
	s_cbranch_vccz .LBB0_1337
	global_store_dwordx4 v[86:87], v[82:85], off
	s_nop 1
	s_mov_b64 s[36:37], 0

.LBB0_1341:
	s_or_b64 exec, exec, s[36:37]
	v_add_u32_e32 v114, 0x80, v174
	v_ashrrev_i32_e32 v115, 31, v114
	s_waitcnt lgkmcnt(0)
	v_lshlrev_b64 v[82:83], 10, v[114:115]
	v_lshl_add_u64 v[82:83], v[82:83], 0, v[172:173]
	v_lshlrev_b64 v[82:83], 1, v[82:83]
	v_lshl_add_u64 v[84:85], s[0:1], 0, v[82:83]
	v_lshl_add_u64 v[86:87], s[12:13], 0, v[82:83]
	v_or_b32_e32 v82, 0x100, v82
	flat_load_dwordx4 v[90:93], v[84:85]
	flat_load_dwordx4 v[94:97], v[86:87]
	v_lshl_add_u64 v[84:85], s[0:1], 0, v[82:83]
	v_lshl_add_u64 v[86:87], s[12:13], 0, v[82:83]
	flat_load_dwordx4 v[82:85], v[84:85]
	s_nop 0
	flat_load_dwordx4 v[86:89], v[86:87]
	v_mul_f32_e32 v78, v191, v78
	v_mul_f32_e32 v78, 0xbfb8aa3b, v78
	v_mul_f32_e32 v79, v191, v79
	v_exp_f32_e32 v78, v78
	v_mul_f32_e32 v79, 0xbfb8aa3b, v79
	v_exp_f32_e32 v79, v79
	v_lshlrev_b32_e32 v116, 16, v106
	v_add_f32_e32 v78, 1.0, v78
	v_rcp_f32_e32 v78, v78
	v_add_f32_e32 v79, 1.0, v79
	v_rcp_f32_e32 v79, v79
	v_lshlrev_b32_e32 v117, 16, v110
	v_fmac_f32_e32 v116, v78, v117
	v_and_b32_e32 v117, 0xffff0000, v106
	v_and_b32_e32 v78, 0xffff0000, v110
	v_fmac_f32_e32 v117, v79, v78
	v_mul_f32_e32 v78, v191, v80
	v_mul_f32_e32 v78, 0xbfb8aa3b, v78
	v_mul_f32_e32 v79, v191, v81
	v_exp_f32_e32 v78, v78
	v_mul_f32_e32 v79, 0xbfb8aa3b, v79
	v_mul_f32_e32 v74, v191, v74
	v_exp_f32_e32 v79, v79
	v_mul_f32_e32 v74, 0xbfb8aa3b, v74
	v_mul_f32_e32 v75, v191, v75
	v_exp_f32_e32 v74, v74
	v_mul_f32_e32 v75, 0xbfb8aa3b, v75
	v_exp_f32_e32 v75, v75
	v_add_f32_e32 v78, 1.0, v78
	v_rcp_f32_e32 v78, v78
	v_add_f32_e32 v79, 1.0, v79
	v_rcp_f32_e32 v79, v79
	v_add_f32_e32 v74, 1.0, v74
	v_rcp_f32_e32 v74, v74
	v_add_f32_e32 v75, 1.0, v75
	v_lshlrev_b32_e32 v106, 16, v107
	v_lshlrev_b32_e32 v80, 16, v111
	v_rcp_f32_e32 v75, v75
	v_fmac_f32_e32 v106, v78, v80
	v_and_b32_e32 v81, 0xffff0000, v107
	v_and_b32_e32 v78, 0xffff0000, v111
	v_fmac_f32_e32 v81, v79, v78
	v_lshlrev_b32_e32 v80, 16, v108
	v_lshlrev_b32_e32 v78, 16, v112
	v_fmac_f32_e32 v80, v74, v78
	v_and_b32_e32 v108, 0xffff0000, v108
	v_and_b32_e32 v74, 0xffff0000, v112
	v_fmac_f32_e32 v108, v75, v74
	v_mul_f32_e32 v74, v191, v76
	v_mul_f32_e32 v74, 0xbfb8aa3b, v74
	v_mul_f32_e32 v75, v191, v77
	v_exp_f32_e32 v74, v74
	v_mul_f32_e32 v75, 0xbfb8aa3b, v75
	v_exp_f32_e32 v75, v75
	v_lshlrev_b32_e32 v107, 16, v109
	v_add_f32_e32 v74, 1.0, v74
	v_rcp_f32_e32 v74, v74
	v_add_f32_e32 v75, 1.0, v75
	v_rcp_f32_e32 v75, v75
	v_lshlrev_b32_e32 v76, 16, v113
	v_lshlrev_b64 v[78:79], 11, v[130:131]
	v_fmac_f32_e32 v107, v74, v76
	v_and_b32_e32 v109, 0xffff0000, v109
	v_and_b32_e32 v74, 0xffff0000, v113
	v_lshl_add_u64 v[78:79], s[14:15], 0, v[78:79]
	v_fmac_f32_e32 v109, v75, v74
	v_lshl_add_u64 v[78:79], v[172:173], 1, v[78:79]
	s_mov_b64 s[36:37], -1
	s_and_b64 vcc, exec, s[6:7]
	v_cvt_pk_bf16_f32 v74, v116, v117
	v_cvt_pk_bf16_f32 v75, v106, v81
	v_cvt_pk_bf16_f32 v76, v80, v108
	v_cvt_pk_bf16_f32 v77, v107, v109
	s_cbranch_vccz .LBB0_1343
	global_store_dwordx4 v[78:79], v[74:77], off
	s_nop 1
	s_mov_b64 s[36:37], 0

.LBB0_1345:
	v_mul_f32_e32 v70, v191, v70
	v_mul_f32_e32 v70, 0xbfb8aa3b, v70
	v_mul_f32_e32 v71, v191, v71
	v_exp_f32_e32 v70, v70
	v_mul_f32_e32 v71, 0xbfb8aa3b, v71
	v_exp_f32_e32 v71, v71
	v_lshlrev_b32_e32 v74, 16, v98
	v_add_f32_e32 v70, 1.0, v70
	v_rcp_f32_e32 v70, v70
	v_add_f32_e32 v71, 1.0, v71
	v_rcp_f32_e32 v71, v71
	v_lshlrev_b32_e32 v75, 16, v102
	v_fmac_f32_e32 v74, v70, v75
	v_and_b32_e32 v76, 0xffff0000, v98
	v_and_b32_e32 v70, 0xffff0000, v102
	v_fmac_f32_e32 v76, v71, v70
	v_mul_f32_e32 v70, v191, v72
	v_mul_f32_e32 v70, 0xbfb8aa3b, v70
	v_mul_f32_e32 v71, v191, v73
	v_exp_f32_e32 v70, v70
	v_mul_f32_e32 v71, 0xbfb8aa3b, v71
	v_mul_f32_e32 v66, v191, v66
	v_exp_f32_e32 v71, v71
	v_mul_f32_e32 v66, 0xbfb8aa3b, v66
	v_mul_f32_e32 v67, v191, v67
	v_exp_f32_e32 v66, v66
	v_mul_f32_e32 v67, 0xbfb8aa3b, v67
	v_exp_f32_e32 v67, v67
	v_add_f32_e32 v70, 1.0, v70
	v_rcp_f32_e32 v70, v70
	v_add_f32_e32 v71, 1.0, v71
	v_rcp_f32_e32 v71, v71
	v_add_f32_e32 v66, 1.0, v66
	v_rcp_f32_e32 v66, v66
	v_add_f32_e32 v67, 1.0, v67
	v_lshlrev_b32_e32 v75, 16, v99
	v_lshlrev_b32_e32 v72, 16, v103
	v_rcp_f32_e32 v67, v67
	v_fmac_f32_e32 v75, v70, v72
	v_and_b32_e32 v73, 0xffff0000, v99
	v_and_b32_e32 v70, 0xffff0000, v103
	v_fmac_f32_e32 v73, v71, v70
	v_lshlrev_b32_e32 v72, 16, v100
	v_lshlrev_b32_e32 v70, 16, v104
	v_fmac_f32_e32 v72, v66, v70
	v_and_b32_e32 v98, 0xffff0000, v100
	v_and_b32_e32 v66, 0xffff0000, v104
	v_fmac_f32_e32 v98, v67, v66
	v_mul_f32_e32 v66, v191, v68
	v_mul_f32_e32 v66, 0xbfb8aa3b, v66
	v_mul_f32_e32 v67, v191, v69
	v_exp_f32_e32 v66, v66
	v_mul_f32_e32 v67, 0xbfb8aa3b, v67
	v_exp_f32_e32 v67, v67
	v_lshlrev_b32_e32 v77, 16, v101
	v_add_f32_e32 v66, 1.0, v66
	v_rcp_f32_e32 v66, v66
	v_add_f32_e32 v67, 1.0, v67
	v_rcp_f32_e32 v67, v67
	v_lshlrev_b32_e32 v68, 16, v105
	v_fmac_f32_e32 v77, v66, v68
	v_and_b32_e32 v99, 0xffff0000, v101
	v_and_b32_e32 v66, 0xffff0000, v105
	v_fmac_f32_e32 v99, v67, v66
	v_lshl_add_u64 v[70:71], v[78:79], 0, s[22:23]
	s_mov_b64 s[36:37], -1
	s_and_b64 vcc, exec, s[6:7]
	v_cvt_pk_bf16_f32 v66, v74, v76
	v_cvt_pk_bf16_f32 v67, v75, v73
	v_cvt_pk_bf16_f32 v68, v72, v98
	v_cvt_pk_bf16_f32 v69, v77, v99
	s_cbranch_vccz .LBB0_1347
	global_store_dwordx4 v[70:71], v[66:69], off
	s_nop 1
	s_mov_b64 s[36:37], 0

.LBB0_1351:
	s_or_b64 exec, exec, s[36:37]
	v_or_b32_e32 v66, 16, v114
	s_waitcnt lgkmcnt(0)
	v_ashrrev_i32_e32 v67, 31, v66
	v_lshlrev_b64 v[66:67], 10, v[66:67]
	v_lshl_add_u64 v[66:67], v[66:67], 0, v[172:173]
	v_lshlrev_b64 v[66:67], 1, v[66:67]
	v_lshl_add_u64 v[68:69], s[0:1], 0, v[66:67]
	v_lshl_add_u64 v[70:71], s[12:13], 0, v[66:67]
	v_or_b32_e32 v66, 0x100, v66
	flat_load_dwordx4 v[74:77], v[68:69]
	flat_load_dwordx4 v[78:81], v[70:71]
	v_lshl_add_u64 v[68:69], s[0:1], 0, v[66:67]
	v_lshl_add_u64 v[70:71], s[12:13], 0, v[66:67]
	flat_load_dwordx4 v[66:69], v[68:69]
	s_nop 0
	flat_load_dwordx4 v[70:73], v[70:71]
	v_mul_f32_e32 v62, v190, v62
	v_mul_f32_e32 v62, 0xbfb8aa3b, v62
	v_mul_f32_e32 v63, v190, v63
	v_exp_f32_e32 v62, v62
	v_mul_f32_e32 v63, 0xbfb8aa3b, v63
	v_exp_f32_e32 v63, v63
	s_waitcnt vmcnt(0)
	v_lshlrev_b32_e32 v98, 16, v90
	v_add_f32_e32 v62, 1.0, v62
	v_rcp_f32_e32 v62, v62
	v_add_f32_e32 v63, 1.0, v63
	v_rcp_f32_e32 v63, v63
	v_lshlrev_b32_e32 v99, 16, v94
	v_fmac_f32_e32 v98, v62, v99
	v_and_b32_e32 v99, 0xffff0000, v90
	v_and_b32_e32 v62, 0xffff0000, v94
	v_fmac_f32_e32 v99, v63, v62
	v_mul_f32_e32 v62, v190, v64
	v_mul_f32_e32 v62, 0xbfb8aa3b, v62
	v_mul_f32_e32 v63, v190, v65
	v_exp_f32_e32 v62, v62
	v_mul_f32_e32 v63, 0xbfb8aa3b, v63
	v_mul_f32_e32 v58, v190, v58
	v_exp_f32_e32 v63, v63
	v_mul_f32_e32 v58, 0xbfb8aa3b, v58
	v_mul_f32_e32 v59, v190, v59
	v_exp_f32_e32 v58, v58
	v_mul_f32_e32 v59, 0xbfb8aa3b, v59
	v_exp_f32_e32 v59, v59
	v_add_f32_e32 v62, 1.0, v62
	v_rcp_f32_e32 v62, v62
	v_add_f32_e32 v63, 1.0, v63
	v_rcp_f32_e32 v63, v63
	v_add_f32_e32 v58, 1.0, v58
	v_rcp_f32_e32 v58, v58
	v_add_f32_e32 v59, 1.0, v59
	v_lshlrev_b32_e32 v90, 16, v91
	v_lshlrev_b32_e32 v64, 16, v95
	v_rcp_f32_e32 v59, v59
	v_fmac_f32_e32 v90, v62, v64
	v_and_b32_e32 v65, 0xffff0000, v91
	v_and_b32_e32 v62, 0xffff0000, v95
	v_fmac_f32_e32 v65, v63, v62
	v_lshlrev_b32_e32 v64, 16, v92
	v_lshlrev_b32_e32 v62, 16, v96
	v_fmac_f32_e32 v64, v58, v62
	v_and_b32_e32 v92, 0xffff0000, v92
	v_and_b32_e32 v58, 0xffff0000, v96
	v_fmac_f32_e32 v92, v59, v58
	v_mul_f32_e32 v58, v190, v60
	v_mul_f32_e32 v58, 0xbfb8aa3b, v58
	v_mul_f32_e32 v59, v190, v61
	v_exp_f32_e32 v58, v58
	v_mul_f32_e32 v59, 0xbfb8aa3b, v59
	v_exp_f32_e32 v59, v59
	v_lshlrev_b32_e32 v91, 16, v93
	v_add_f32_e32 v58, 1.0, v58
	v_rcp_f32_e32 v58, v58
	v_add_f32_e32 v59, 1.0, v59
	v_rcp_f32_e32 v59, v59
	v_lshlrev_b32_e32 v60, 16, v97
	v_lshlrev_b64 v[62:63], 11, v[114:115]
	v_fmac_f32_e32 v91, v58, v60
	v_and_b32_e32 v93, 0xffff0000, v93
	v_and_b32_e32 v58, 0xffff0000, v97
	v_lshl_add_u64 v[62:63], s[14:15], 0, v[62:63]
	v_fmac_f32_e32 v93, v59, v58
	v_lshl_add_u64 v[62:63], v[172:173], 1, v[62:63]
	s_mov_b64 s[36:37], -1
	s_and_b64 vcc, exec, s[6:7]
	v_cvt_pk_bf16_f32 v58, v98, v99
	v_cvt_pk_bf16_f32 v59, v90, v65
	v_cvt_pk_bf16_f32 v60, v64, v92
	v_cvt_pk_bf16_f32 v61, v91, v93
	s_cbranch_vccz .LBB0_1353
	global_store_dwordx4 v[62:63], v[58:61], off
	s_nop 1
	s_mov_b64 s[36:37], 0

.LBB0_1355:
	v_mul_f32_e32 v54, v190, v54
	v_mul_f32_e32 v54, 0xbfb8aa3b, v54
	v_mul_f32_e32 v55, v190, v55
	v_exp_f32_e32 v54, v54
	v_mul_f32_e32 v55, 0xbfb8aa3b, v55
	v_exp_f32_e32 v55, v55
	v_lshlrev_b32_e32 v58, 16, v82
	v_add_f32_e32 v54, 1.0, v54
	v_rcp_f32_e32 v54, v54
	v_add_f32_e32 v55, 1.0, v55
	v_rcp_f32_e32 v55, v55
	v_lshlrev_b32_e32 v59, 16, v86
	v_fmac_f32_e32 v58, v54, v59
	v_and_b32_e32 v60, 0xffff0000, v82
	v_and_b32_e32 v54, 0xffff0000, v86
	v_fmac_f32_e32 v60, v55, v54
	v_mul_f32_e32 v54, v190, v56
	v_mul_f32_e32 v54, 0xbfb8aa3b, v54
	v_mul_f32_e32 v55, v190, v57
	v_exp_f32_e32 v54, v54
	v_mul_f32_e32 v55, 0xbfb8aa3b, v55
	v_mul_f32_e32 v50, v190, v50
	v_exp_f32_e32 v55, v55
	v_mul_f32_e32 v50, 0xbfb8aa3b, v50
	v_mul_f32_e32 v51, v190, v51
	v_exp_f32_e32 v50, v50
	v_mul_f32_e32 v51, 0xbfb8aa3b, v51
	v_exp_f32_e32 v51, v51
	v_add_f32_e32 v54, 1.0, v54
	v_rcp_f32_e32 v54, v54
	v_add_f32_e32 v55, 1.0, v55
	v_rcp_f32_e32 v55, v55
	v_add_f32_e32 v50, 1.0, v50
	v_rcp_f32_e32 v50, v50
	v_add_f32_e32 v51, 1.0, v51
	v_lshlrev_b32_e32 v59, 16, v83
	v_lshlrev_b32_e32 v56, 16, v87
	v_rcp_f32_e32 v51, v51
	v_fmac_f32_e32 v59, v54, v56
	v_and_b32_e32 v57, 0xffff0000, v83
	v_and_b32_e32 v54, 0xffff0000, v87
	v_fmac_f32_e32 v57, v55, v54
	v_lshlrev_b32_e32 v56, 16, v84
	v_lshlrev_b32_e32 v54, 16, v88
	v_fmac_f32_e32 v56, v50, v54
	v_and_b32_e32 v82, 0xffff0000, v84
	v_and_b32_e32 v50, 0xffff0000, v88
	v_fmac_f32_e32 v82, v51, v50
	v_mul_f32_e32 v50, v190, v52
	v_mul_f32_e32 v50, 0xbfb8aa3b, v50
	v_mul_f32_e32 v51, v190, v53
	v_exp_f32_e32 v50, v50
	v_mul_f32_e32 v51, 0xbfb8aa3b, v51
	v_exp_f32_e32 v51, v51
	v_lshlrev_b32_e32 v61, 16, v85
	v_add_f32_e32 v50, 1.0, v50
	v_rcp_f32_e32 v50, v50
	v_add_f32_e32 v51, 1.0, v51
	v_rcp_f32_e32 v51, v51
	v_lshlrev_b32_e32 v52, 16, v89
	v_fmac_f32_e32 v61, v50, v52
	v_and_b32_e32 v83, 0xffff0000, v85
	v_and_b32_e32 v50, 0xffff0000, v89
	v_fmac_f32_e32 v83, v51, v50
	v_lshl_add_u64 v[54:55], v[62:63], 0, s[22:23]
	s_mov_b64 s[36:37], -1
	s_and_b64 vcc, exec, s[6:7]
	v_cvt_pk_bf16_f32 v50, v58, v60
	v_cvt_pk_bf16_f32 v51, v59, v57
	v_cvt_pk_bf16_f32 v52, v56, v82
	v_cvt_pk_bf16_f32 v53, v61, v83
	s_cbranch_vccz .LBB0_1357
	global_store_dwordx4 v[54:55], v[50:53], off
	s_nop 1
	s_mov_b64 s[36:37], 0

.LBB0_1361:
	s_or_b64 exec, exec, s[36:37]
	v_or_b32_e32 v50, 32, v114
	s_waitcnt lgkmcnt(0)
	v_ashrrev_i32_e32 v51, 31, v50
	v_lshlrev_b64 v[50:51], 10, v[50:51]
	v_lshl_add_u64 v[50:51], v[50:51], 0, v[172:173]
	v_lshlrev_b64 v[50:51], 1, v[50:51]
	v_lshl_add_u64 v[52:53], s[0:1], 0, v[50:51]
	v_lshl_add_u64 v[54:55], s[12:13], 0, v[50:51]
	v_or_b32_e32 v50, 0x100, v50
	flat_load_dwordx4 v[58:61], v[52:53]
	flat_load_dwordx4 v[62:65], v[54:55]
	v_lshl_add_u64 v[52:53], s[0:1], 0, v[50:51]
	v_lshl_add_u64 v[54:55], s[12:13], 0, v[50:51]
	flat_load_dwordx4 v[50:53], v[52:53]
	s_nop 0
	flat_load_dwordx4 v[54:57], v[54:55]
	v_mul_f32_e32 v46, v189, v46
	v_mul_f32_e32 v46, 0xbfb8aa3b, v46
	v_mul_f32_e32 v47, v189, v47
	v_exp_f32_e32 v46, v46
	v_mul_f32_e32 v47, 0xbfb8aa3b, v47
	v_exp_f32_e32 v47, v47
	v_lshlrev_b32_e32 v84, 16, v74
	v_add_f32_e32 v46, 1.0, v46
	v_rcp_f32_e32 v46, v46
	v_add_f32_e32 v47, 1.0, v47
	v_rcp_f32_e32 v47, v47
	v_lshlrev_b32_e32 v85, 16, v78
	v_fmac_f32_e32 v84, v46, v85
	v_and_b32_e32 v85, 0xffff0000, v74
	v_and_b32_e32 v46, 0xffff0000, v78
	v_fmac_f32_e32 v85, v47, v46
	v_mul_f32_e32 v46, v189, v48
	v_mul_f32_e32 v46, 0xbfb8aa3b, v46
	v_mul_f32_e32 v47, v189, v49
	v_exp_f32_e32 v46, v46
	v_mul_f32_e32 v47, 0xbfb8aa3b, v47
	v_mul_f32_e32 v42, v189, v42
	v_exp_f32_e32 v47, v47
	v_mul_f32_e32 v42, 0xbfb8aa3b, v42
	v_mul_f32_e32 v43, v189, v43
	v_exp_f32_e32 v42, v42
	v_mul_f32_e32 v43, 0xbfb8aa3b, v43
	v_exp_f32_e32 v43, v43
	v_add_f32_e32 v46, 1.0, v46
	v_rcp_f32_e32 v46, v46
	v_add_f32_e32 v47, 1.0, v47
	v_rcp_f32_e32 v47, v47
	v_add_f32_e32 v42, 1.0, v42
	v_rcp_f32_e32 v42, v42
	v_add_f32_e32 v43, 1.0, v43
	v_lshlrev_b32_e32 v74, 16, v75
	v_lshlrev_b32_e32 v48, 16, v79
	v_rcp_f32_e32 v43, v43
	v_fmac_f32_e32 v74, v46, v48
	v_and_b32_e32 v49, 0xffff0000, v75
	v_and_b32_e32 v46, 0xffff0000, v79
	v_fmac_f32_e32 v49, v47, v46
	v_lshlrev_b32_e32 v48, 16, v76
	v_lshlrev_b32_e32 v46, 16, v80
	v_fmac_f32_e32 v48, v42, v46
	v_and_b32_e32 v76, 0xffff0000, v76
	v_and_b32_e32 v42, 0xffff0000, v80
	v_fmac_f32_e32 v76, v43, v42
	v_mul_f32_e32 v42, v189, v44
	v_mul_f32_e32 v42, 0xbfb8aa3b, v42
	v_mul_f32_e32 v43, v189, v45
	v_exp_f32_e32 v42, v42
	v_mul_f32_e32 v43, 0xbfb8aa3b, v43
	v_exp_f32_e32 v43, v43
	v_add_u32_e32 v82, 0x90, v174
	v_add_f32_e32 v42, 1.0, v42
	v_rcp_f32_e32 v42, v42
	v_add_f32_e32 v43, 1.0, v43
	v_rcp_f32_e32 v43, v43
	v_ashrrev_i32_e32 v83, 31, v82
	v_lshlrev_b32_e32 v75, 16, v77
	v_lshlrev_b32_e32 v44, 16, v81
	v_lshlrev_b64 v[46:47], 11, v[82:83]
	v_fmac_f32_e32 v75, v42, v44
	v_and_b32_e32 v77, 0xffff0000, v77
	v_and_b32_e32 v42, 0xffff0000, v81
	v_lshl_add_u64 v[46:47], s[14:15], 0, v[46:47]
	v_fmac_f32_e32 v77, v43, v42
	v_lshl_add_u64 v[46:47], v[172:173], 1, v[46:47]
	s_mov_b64 s[36:37], -1
	s_and_b64 vcc, exec, s[6:7]
	v_cvt_pk_bf16_f32 v42, v84, v85
	v_cvt_pk_bf16_f32 v43, v74, v49
	v_cvt_pk_bf16_f32 v44, v48, v76
	v_cvt_pk_bf16_f32 v45, v75, v77
	s_cbranch_vccz .LBB0_1363
	global_store_dwordx4 v[46:47], v[42:45], off
	s_nop 1
	s_mov_b64 s[36:37], 0

.LBB0_1365:
	v_mul_f32_e32 v38, v189, v38
	v_mul_f32_e32 v38, 0xbfb8aa3b, v38
	v_mul_f32_e32 v39, v189, v39
	v_exp_f32_e32 v38, v38
	v_mul_f32_e32 v39, 0xbfb8aa3b, v39
	v_exp_f32_e32 v39, v39
	v_lshlrev_b32_e32 v42, 16, v66
	v_add_f32_e32 v38, 1.0, v38
	v_rcp_f32_e32 v38, v38
	v_add_f32_e32 v39, 1.0, v39
	v_rcp_f32_e32 v39, v39
	v_lshlrev_b32_e32 v43, 16, v70
	v_fmac_f32_e32 v42, v38, v43
	v_and_b32_e32 v44, 0xffff0000, v66
	v_and_b32_e32 v38, 0xffff0000, v70
	v_fmac_f32_e32 v44, v39, v38
	v_mul_f32_e32 v38, v189, v40
	v_mul_f32_e32 v38, 0xbfb8aa3b, v38
	v_mul_f32_e32 v39, v189, v41
	v_exp_f32_e32 v38, v38
	v_mul_f32_e32 v39, 0xbfb8aa3b, v39
	v_mul_f32_e32 v34, v189, v34
	v_exp_f32_e32 v39, v39
	v_mul_f32_e32 v34, 0xbfb8aa3b, v34
	v_mul_f32_e32 v35, v189, v35
	v_exp_f32_e32 v34, v34
	v_mul_f32_e32 v35, 0xbfb8aa3b, v35
	v_exp_f32_e32 v35, v35
	v_add_f32_e32 v38, 1.0, v38
	v_rcp_f32_e32 v38, v38
	v_add_f32_e32 v39, 1.0, v39
	v_rcp_f32_e32 v39, v39
	v_add_f32_e32 v34, 1.0, v34
	v_rcp_f32_e32 v34, v34
	v_add_f32_e32 v35, 1.0, v35
	v_lshlrev_b32_e32 v43, 16, v67
	v_lshlrev_b32_e32 v40, 16, v71
	v_rcp_f32_e32 v35, v35
	v_fmac_f32_e32 v43, v38, v40
	v_and_b32_e32 v41, 0xffff0000, v67
	v_and_b32_e32 v38, 0xffff0000, v71
	v_fmac_f32_e32 v41, v39, v38
	v_lshlrev_b32_e32 v40, 16, v68
	v_lshlrev_b32_e32 v38, 16, v72
	v_fmac_f32_e32 v40, v34, v38
	v_and_b32_e32 v66, 0xffff0000, v68
	v_and_b32_e32 v34, 0xffff0000, v72
	v_fmac_f32_e32 v66, v35, v34
	v_mul_f32_e32 v34, v189, v36
	v_mul_f32_e32 v34, 0xbfb8aa3b, v34
	v_mul_f32_e32 v35, v189, v37
	v_exp_f32_e32 v34, v34
	v_mul_f32_e32 v35, 0xbfb8aa3b, v35
	v_exp_f32_e32 v35, v35
	v_lshlrev_b32_e32 v45, 16, v69
	v_add_f32_e32 v34, 1.0, v34
	v_rcp_f32_e32 v34, v34
	v_add_f32_e32 v35, 1.0, v35
	v_rcp_f32_e32 v35, v35
	v_lshlrev_b32_e32 v36, 16, v73
	v_fmac_f32_e32 v45, v34, v36
	v_and_b32_e32 v67, 0xffff0000, v69
	v_and_b32_e32 v34, 0xffff0000, v73
	v_fmac_f32_e32 v67, v35, v34
	v_lshl_add_u64 v[38:39], v[46:47], 0, s[22:23]
	s_mov_b64 s[36:37], -1
	s_and_b64 vcc, exec, s[6:7]
	v_cvt_pk_bf16_f32 v34, v42, v44
	v_cvt_pk_bf16_f32 v35, v43, v41
	v_cvt_pk_bf16_f32 v36, v40, v66
	v_cvt_pk_bf16_f32 v37, v45, v67
	s_cbranch_vccz .LBB0_1367
	global_store_dwordx4 v[38:39], v[34:37], off
	s_nop 1
	s_mov_b64 s[36:37], 0

.LBB0_1371:
	s_or_b64 exec, exec, s[36:37]
	v_or_b32_e32 v34, 48, v114
	s_waitcnt lgkmcnt(0)
	v_ashrrev_i32_e32 v35, 31, v34
	v_lshlrev_b64 v[34:35], 10, v[34:35]
	v_lshl_add_u64 v[34:35], v[34:35], 0, v[172:173]
	v_lshlrev_b64 v[34:35], 1, v[34:35]
	v_lshl_add_u64 v[36:37], s[0:1], 0, v[34:35]
	v_lshl_add_u64 v[38:39], s[12:13], 0, v[34:35]
	v_or_b32_e32 v34, 0x100, v34
	flat_load_dwordx4 v[42:45], v[36:37]
	flat_load_dwordx4 v[46:49], v[38:39]
	v_lshl_add_u64 v[36:37], s[0:1], 0, v[34:35]
	v_lshl_add_u64 v[38:39], s[12:13], 0, v[34:35]
	flat_load_dwordx4 v[34:37], v[36:37]
	s_nop 0
	flat_load_dwordx4 v[38:41], v[38:39]
	v_mul_f32_e32 v30, v188, v30
	v_mul_f32_e32 v30, 0xbfb8aa3b, v30
	v_mul_f32_e32 v31, v188, v31
	v_exp_f32_e32 v30, v30
	v_mul_f32_e32 v31, 0xbfb8aa3b, v31
	v_exp_f32_e32 v31, v31
	s_waitcnt vmcnt(0)
	v_lshlrev_b32_e32 v68, 16, v58
	v_add_f32_e32 v30, 1.0, v30
	v_rcp_f32_e32 v30, v30
	v_add_f32_e32 v31, 1.0, v31
	v_rcp_f32_e32 v31, v31
	v_lshlrev_b32_e32 v69, 16, v62
	v_fmac_f32_e32 v68, v30, v69
	v_and_b32_e32 v69, 0xffff0000, v58
	v_and_b32_e32 v30, 0xffff0000, v62
	v_fmac_f32_e32 v69, v31, v30
	v_mul_f32_e32 v30, v188, v32
	v_mul_f32_e32 v30, 0xbfb8aa3b, v30
	v_mul_f32_e32 v31, v188, v33
	v_exp_f32_e32 v30, v30
	v_mul_f32_e32 v31, 0xbfb8aa3b, v31
	v_mul_f32_e32 v26, v188, v26
	v_exp_f32_e32 v31, v31
	v_mul_f32_e32 v26, 0xbfb8aa3b, v26
	v_mul_f32_e32 v27, v188, v27
	v_exp_f32_e32 v26, v26
	v_mul_f32_e32 v27, 0xbfb8aa3b, v27
	v_exp_f32_e32 v27, v27
	v_add_f32_e32 v30, 1.0, v30
	v_rcp_f32_e32 v30, v30
	v_add_f32_e32 v31, 1.0, v31
	v_rcp_f32_e32 v31, v31
	v_add_f32_e32 v26, 1.0, v26
	v_rcp_f32_e32 v26, v26
	v_add_f32_e32 v27, 1.0, v27
	v_lshlrev_b32_e32 v58, 16, v59
	v_lshlrev_b32_e32 v32, 16, v63
	v_rcp_f32_e32 v27, v27
	v_fmac_f32_e32 v58, v30, v32
	v_and_b32_e32 v33, 0xffff0000, v59
	v_and_b32_e32 v30, 0xffff0000, v63
	v_fmac_f32_e32 v33, v31, v30
	v_lshlrev_b32_e32 v32, 16, v60
	v_lshlrev_b32_e32 v30, 16, v64
	v_fmac_f32_e32 v32, v26, v30
	v_and_b32_e32 v60, 0xffff0000, v60
	v_and_b32_e32 v26, 0xffff0000, v64
	v_fmac_f32_e32 v60, v27, v26
	v_mul_f32_e32 v26, v188, v28
	v_mul_f32_e32 v26, 0xbfb8aa3b, v26
	v_mul_f32_e32 v27, v188, v29
	v_exp_f32_e32 v26, v26
	v_mul_f32_e32 v27, 0xbfb8aa3b, v27
	v_exp_f32_e32 v27, v27
	v_add_u32_e32 v66, 0xa0, v174
	v_add_f32_e32 v26, 1.0, v26
	v_rcp_f32_e32 v26, v26
	v_add_f32_e32 v27, 1.0, v27
	v_rcp_f32_e32 v27, v27
	v_ashrrev_i32_e32 v67, 31, v66
	v_lshlrev_b32_e32 v59, 16, v61
	v_lshlrev_b32_e32 v28, 16, v65
	v_lshlrev_b64 v[30:31], 11, v[66:67]
	v_fmac_f32_e32 v59, v26, v28
	v_and_b32_e32 v61, 0xffff0000, v61
	v_and_b32_e32 v26, 0xffff0000, v65
	v_lshl_add_u64 v[30:31], s[14:15], 0, v[30:31]
	v_fmac_f32_e32 v61, v27, v26
	v_lshl_add_u64 v[30:31], v[172:173], 1, v[30:31]
	s_mov_b64 s[36:37], -1
	s_and_b64 vcc, exec, s[6:7]
	v_cvt_pk_bf16_f32 v26, v68, v69
	v_cvt_pk_bf16_f32 v27, v58, v33
	v_cvt_pk_bf16_f32 v28, v32, v60
	v_cvt_pk_bf16_f32 v29, v59, v61
	s_cbranch_vccz .LBB0_1373
	global_store_dwordx4 v[30:31], v[26:29], off
	s_nop 1
	s_mov_b64 s[36:37], 0

.LBB0_1375:
	v_mul_f32_e32 v22, v188, v22
	v_mul_f32_e32 v22, 0xbfb8aa3b, v22
	v_mul_f32_e32 v23, v188, v23
	v_exp_f32_e32 v22, v22
	v_mul_f32_e32 v23, 0xbfb8aa3b, v23
	v_exp_f32_e32 v23, v23
	v_lshlrev_b32_e32 v26, 16, v50
	v_add_f32_e32 v22, 1.0, v22
	v_rcp_f32_e32 v22, v22
	v_add_f32_e32 v23, 1.0, v23
	v_rcp_f32_e32 v23, v23
	v_lshlrev_b32_e32 v27, 16, v54
	v_fmac_f32_e32 v26, v22, v27
	v_and_b32_e32 v28, 0xffff0000, v50
	v_and_b32_e32 v22, 0xffff0000, v54
	v_fmac_f32_e32 v28, v23, v22
	v_mul_f32_e32 v22, v188, v24
	v_mul_f32_e32 v22, 0xbfb8aa3b, v22
	v_mul_f32_e32 v23, v188, v25
	v_exp_f32_e32 v22, v22
	v_mul_f32_e32 v23, 0xbfb8aa3b, v23
	v_mul_f32_e32 v18, v188, v18
	v_exp_f32_e32 v23, v23
	v_mul_f32_e32 v18, 0xbfb8aa3b, v18
	v_mul_f32_e32 v19, v188, v19
	v_exp_f32_e32 v18, v18
	v_mul_f32_e32 v19, 0xbfb8aa3b, v19
	v_exp_f32_e32 v19, v19
	v_add_f32_e32 v22, 1.0, v22
	v_rcp_f32_e32 v22, v22
	v_add_f32_e32 v23, 1.0, v23
	v_rcp_f32_e32 v23, v23
	v_add_f32_e32 v18, 1.0, v18
	v_rcp_f32_e32 v18, v18
	v_add_f32_e32 v19, 1.0, v19
	v_lshlrev_b32_e32 v27, 16, v51
	v_lshlrev_b32_e32 v24, 16, v55
	v_rcp_f32_e32 v19, v19
	v_fmac_f32_e32 v27, v22, v24
	v_and_b32_e32 v25, 0xffff0000, v51
	v_and_b32_e32 v22, 0xffff0000, v55
	v_fmac_f32_e32 v25, v23, v22
	v_lshlrev_b32_e32 v24, 16, v52
	v_lshlrev_b32_e32 v22, 16, v56
	v_fmac_f32_e32 v24, v18, v22
	v_and_b32_e32 v50, 0xffff0000, v52
	v_and_b32_e32 v18, 0xffff0000, v56
	v_fmac_f32_e32 v50, v19, v18
	v_mul_f32_e32 v18, v188, v20
	v_mul_f32_e32 v18, 0xbfb8aa3b, v18
	v_mul_f32_e32 v19, v188, v21
	v_exp_f32_e32 v18, v18
	v_mul_f32_e32 v19, 0xbfb8aa3b, v19
	v_exp_f32_e32 v19, v19
	v_lshlrev_b32_e32 v29, 16, v53
	v_add_f32_e32 v18, 1.0, v18
	v_rcp_f32_e32 v18, v18
	v_add_f32_e32 v19, 1.0, v19
	v_rcp_f32_e32 v19, v19
	v_lshlrev_b32_e32 v20, 16, v57
	v_fmac_f32_e32 v29, v18, v20
	v_and_b32_e32 v51, 0xffff0000, v53
	v_and_b32_e32 v18, 0xffff0000, v57
	v_fmac_f32_e32 v51, v19, v18
	v_lshl_add_u64 v[22:23], v[30:31], 0, s[22:23]
	s_mov_b64 s[36:37], -1
	s_and_b64 vcc, exec, s[6:7]
	v_cvt_pk_bf16_f32 v18, v26, v28
	v_cvt_pk_bf16_f32 v19, v27, v25
	v_cvt_pk_bf16_f32 v20, v24, v50
	v_cvt_pk_bf16_f32 v21, v29, v51
	s_cbranch_vccz .LBB0_1377
	global_store_dwordx4 v[22:23], v[18:21], off
	s_nop 1
	s_mov_b64 s[36:37], 0

.LBB0_1381:
	s_or_b64 exec, exec, s[36:37]
	v_mul_f32_e32 v14, v187, v14
	v_mul_f32_e32 v14, 0xbfb8aa3b, v14
	v_mul_f32_e32 v15, v187, v15
	v_exp_f32_e32 v14, v14
	v_mul_f32_e32 v15, 0xbfb8aa3b, v15
	v_exp_f32_e32 v15, v15
	v_lshlrev_b32_e32 v20, 16, v42
	v_add_f32_e32 v14, 1.0, v14
	v_rcp_f32_e32 v14, v14
	v_add_f32_e32 v15, 1.0, v15
	v_rcp_f32_e32 v15, v15
	v_lshlrev_b32_e32 v21, 16, v46
	v_fmac_f32_e32 v20, v14, v21
	v_and_b32_e32 v22, 0xffff0000, v42
	v_and_b32_e32 v14, 0xffff0000, v46
	v_fmac_f32_e32 v22, v15, v14
	v_mul_f32_e32 v14, v187, v16
	v_mul_f32_e32 v14, 0xbfb8aa3b, v14
	v_mul_f32_e32 v15, v187, v17
	v_exp_f32_e32 v14, v14
	v_mul_f32_e32 v15, 0xbfb8aa3b, v15
	v_mul_f32_e32 v10, v187, v10
	v_exp_f32_e32 v15, v15
	v_mul_f32_e32 v10, 0xbfb8aa3b, v10
	v_mul_f32_e32 v11, v187, v11
	v_exp_f32_e32 v10, v10
	v_mul_f32_e32 v11, 0xbfb8aa3b, v11
	v_exp_f32_e32 v11, v11
	v_add_f32_e32 v14, 1.0, v14
	v_rcp_f32_e32 v14, v14
	v_add_f32_e32 v15, 1.0, v15
	v_rcp_f32_e32 v15, v15
	v_add_f32_e32 v10, 1.0, v10
	v_rcp_f32_e32 v10, v10
	v_add_f32_e32 v11, 1.0, v11
	v_lshlrev_b32_e32 v21, 16, v43
	v_lshlrev_b32_e32 v16, 16, v47
	v_rcp_f32_e32 v11, v11
	v_fmac_f32_e32 v21, v14, v16
	v_and_b32_e32 v17, 0xffff0000, v43
	v_and_b32_e32 v14, 0xffff0000, v47
	v_fmac_f32_e32 v17, v15, v14
	v_lshlrev_b32_e32 v16, 16, v44
	v_lshlrev_b32_e32 v14, 16, v48
	v_fmac_f32_e32 v16, v10, v14
	v_and_b32_e32 v24, 0xffff0000, v44
	v_and_b32_e32 v10, 0xffff0000, v48
	v_fmac_f32_e32 v24, v11, v10
	v_mul_f32_e32 v10, v187, v12
	v_mul_f32_e32 v10, 0xbfb8aa3b, v10
	v_mul_f32_e32 v11, v187, v13
	v_exp_f32_e32 v10, v10
	v_mul_f32_e32 v11, 0xbfb8aa3b, v11
	v_exp_f32_e32 v11, v11
	v_add_u32_e32 v18, 0xb0, v174
	v_add_f32_e32 v10, 1.0, v10
	v_rcp_f32_e32 v10, v10
	v_add_f32_e32 v11, 1.0, v11
	v_rcp_f32_e32 v11, v11
	s_waitcnt lgkmcnt(0)
	v_ashrrev_i32_e32 v19, 31, v18
	v_lshlrev_b32_e32 v23, 16, v45
	v_lshlrev_b32_e32 v12, 16, v49
	v_lshlrev_b64 v[14:15], 11, v[18:19]
	v_fmac_f32_e32 v23, v10, v12
	v_and_b32_e32 v25, 0xffff0000, v45
	v_and_b32_e32 v10, 0xffff0000, v49
	v_lshl_add_u64 v[14:15], s[14:15], 0, v[14:15]
	v_fmac_f32_e32 v25, v11, v10
	v_lshl_add_u64 v[14:15], v[172:173], 1, v[14:15]
	s_mov_b64 s[36:37], -1
	s_and_b64 vcc, exec, s[6:7]
	v_cvt_pk_bf16_f32 v10, v20, v22
	v_cvt_pk_bf16_f32 v11, v21, v17
	v_cvt_pk_bf16_f32 v12, v16, v24
	v_cvt_pk_bf16_f32 v13, v23, v25
	s_cbranch_vccz .LBB0_1383
	global_store_dwordx4 v[14:15], v[10:13], off
	s_nop 1
	s_mov_b64 s[36:37], 0

.LBB0_1385:
	v_mul_f32_e32 v6, v187, v6
	v_mul_f32_e32 v6, 0xbfb8aa3b, v6
	v_mul_f32_e32 v7, v187, v7
	v_exp_f32_e32 v6, v6
	v_mul_f32_e32 v7, 0xbfb8aa3b, v7
	v_exp_f32_e32 v7, v7
	v_lshlrev_b32_e32 v10, 16, v34
	v_add_f32_e32 v6, 1.0, v6
	v_rcp_f32_e32 v6, v6
	v_add_f32_e32 v7, 1.0, v7
	v_rcp_f32_e32 v7, v7
	v_lshlrev_b32_e32 v11, 16, v38
	v_fmac_f32_e32 v10, v6, v11
	v_and_b32_e32 v12, 0xffff0000, v34
	v_and_b32_e32 v6, 0xffff0000, v38
	v_fmac_f32_e32 v12, v7, v6
	v_mul_f32_e32 v6, v187, v8
	v_mul_f32_e32 v6, 0xbfb8aa3b, v6
	v_mul_f32_e32 v7, v187, v9
	v_exp_f32_e32 v6, v6
	v_mul_f32_e32 v7, 0xbfb8aa3b, v7
	v_mul_f32_e32 v2, v187, v2
	v_exp_f32_e32 v7, v7
	v_mul_f32_e32 v2, 0xbfb8aa3b, v2
	v_mul_f32_e32 v3, v187, v3
	v_exp_f32_e32 v2, v2
	v_mul_f32_e32 v3, 0xbfb8aa3b, v3
	v_exp_f32_e32 v3, v3
	v_add_f32_e32 v6, 1.0, v6
	v_rcp_f32_e32 v6, v6
	v_add_f32_e32 v7, 1.0, v7
	v_rcp_f32_e32 v7, v7
	v_add_f32_e32 v2, 1.0, v2
	v_rcp_f32_e32 v2, v2
	v_add_f32_e32 v3, 1.0, v3
	v_lshlrev_b32_e32 v11, 16, v35
	v_lshlrev_b32_e32 v8, 16, v39
	v_rcp_f32_e32 v3, v3
	v_fmac_f32_e32 v11, v6, v8
	v_and_b32_e32 v9, 0xffff0000, v35
	v_and_b32_e32 v6, 0xffff0000, v39
	v_fmac_f32_e32 v9, v7, v6
	v_lshlrev_b32_e32 v8, 16, v36
	v_lshlrev_b32_e32 v6, 16, v40
	v_fmac_f32_e32 v8, v2, v6
	v_and_b32_e32 v26, 0xffff0000, v36
	v_and_b32_e32 v2, 0xffff0000, v40
	v_fmac_f32_e32 v26, v3, v2
	v_mul_f32_e32 v2, v187, v4
	v_mul_f32_e32 v2, 0xbfb8aa3b, v2
	v_mul_f32_e32 v3, v187, v5
	v_exp_f32_e32 v2, v2
	v_mul_f32_e32 v3, 0xbfb8aa3b, v3
	v_exp_f32_e32 v3, v3
	v_lshlrev_b32_e32 v13, 16, v37
	v_add_f32_e32 v2, 1.0, v2
	v_rcp_f32_e32 v2, v2
	v_add_f32_e32 v3, 1.0, v3
	v_rcp_f32_e32 v3, v3
	v_lshlrev_b32_e32 v4, 16, v41
	v_fmac_f32_e32 v13, v2, v4
	v_and_b32_e32 v27, 0xffff0000, v37
	v_and_b32_e32 v2, 0xffff0000, v41
	v_fmac_f32_e32 v27, v3, v2
	v_lshl_add_u64 v[6:7], v[14:15], 0, s[22:23]
	s_mov_b64 s[36:37], -1
	s_and_b64 vcc, exec, s[6:7]
	v_cvt_pk_bf16_f32 v2, v10, v12
	v_cvt_pk_bf16_f32 v3, v11, v9
	v_cvt_pk_bf16_f32 v4, v8, v26
	v_cvt_pk_bf16_f32 v5, v13, v27
	s_cbranch_vccz .LBB0_1387
	global_store_dwordx4 v[6:7], v[2:5], off
	s_nop 1
	s_mov_b64 s[36:37], 0

.LBB0_2355:
	v_lshl_add_u32 v142, s30, 8, v144
	v_ashrrev_i32_e32 v143, 31, v142
	v_lshl_or_b32 v140, s34, 8, v146
	v_cvt_pk_bf16_f32 v124, v124, v125
	v_cvt_pk_bf16_f32 v125, v126, v127
	v_cvt_pk_bf16_f32 v126, v120, v121
	v_lshlrev_b64 v[120:121], 11, v[142:143]
	v_ashrrev_i32_e32 v141, 31, v140
	v_lshl_add_u64 v[120:121], s[6:7], 0, v[120:121]
	v_lshl_add_u64 v[120:121], v[140:141], 1, v[120:121]
	s_andn2_b64 vcc, exec, s[2:3]
	s_mov_b64 s[30:31], -1
	v_cvt_pk_bf16_f32 v127, v122, v123
	s_cbranch_vccnz .LBB0_2357
	global_store_dwordx4 v[120:121], v[124:127], off
	s_nop 1
	s_mov_b64 s[30:31], 0

.LBB0_2359:
	v_cvt_pk_bf16_f32 v116, v116, v117
	v_cvt_pk_bf16_f32 v117, v118, v119
	v_cvt_pk_bf16_f32 v118, v112, v113
	v_lshl_add_u64 v[112:113], v[120:121], 0, s[12:13]
	s_mov_b64 s[30:31], -1
	s_and_b64 vcc, exec, s[2:3]
	v_cvt_pk_bf16_f32 v119, v114, v115
	s_cbranch_vccz .LBB0_2361
	global_store_dwordx4 v[112:113], v[116:119], off
	s_nop 1
	s_mov_b64 s[30:31], 0

.LBB0_2363:
	v_or_b32_e32 v112, 16, v142
	v_ashrrev_i32_e32 v113, 31, v112
	v_cvt_pk_bf16_f32 v108, v108, v109
	v_cvt_pk_bf16_f32 v109, v110, v111
	v_cvt_pk_bf16_f32 v110, v104, v105
	v_lshlrev_b64 v[104:105], 11, v[112:113]
	v_lshl_add_u64 v[104:105], s[6:7], 0, v[104:105]
	v_lshl_add_u64 v[104:105], v[140:141], 1, v[104:105]
	s_mov_b64 s[30:31], -1
	s_and_b64 vcc, exec, s[2:3]
	v_cvt_pk_bf16_f32 v111, v106, v107
	s_cbranch_vccz .LBB0_2365
	global_store_dwordx4 v[104:105], v[108:111], off
	s_nop 1
	s_mov_b64 s[30:31], 0

.LBB0_2367:
	v_cvt_pk_bf16_f32 v100, v100, v101
	v_cvt_pk_bf16_f32 v101, v102, v103
	v_cvt_pk_bf16_f32 v102, v96, v97
	v_lshl_add_u64 v[96:97], v[104:105], 0, s[12:13]
	s_mov_b64 s[30:31], -1
	s_and_b64 vcc, exec, s[2:3]
	v_cvt_pk_bf16_f32 v103, v98, v99
	s_cbranch_vccz .LBB0_2369
	global_store_dwordx4 v[96:97], v[100:103], off
	s_nop 1
	s_mov_b64 s[30:31], 0

.LBB0_2371:
	v_or_b32_e32 v96, 32, v142
	v_ashrrev_i32_e32 v97, 31, v96
	v_cvt_pk_bf16_f32 v92, v92, v93
	v_cvt_pk_bf16_f32 v93, v94, v95
	v_cvt_pk_bf16_f32 v94, v88, v89
	v_lshlrev_b64 v[88:89], 11, v[96:97]
	v_lshl_add_u64 v[88:89], s[6:7], 0, v[88:89]
	v_lshl_add_u64 v[88:89], v[140:141], 1, v[88:89]
	s_mov_b64 s[30:31], -1
	s_and_b64 vcc, exec, s[2:3]
	v_cvt_pk_bf16_f32 v95, v90, v91
	s_cbranch_vccz .LBB0_2373
	global_store_dwordx4 v[88:89], v[92:95], off
	s_nop 1
	s_mov_b64 s[30:31], 0

.LBB0_2375:
	v_cvt_pk_bf16_f32 v84, v84, v85
	v_cvt_pk_bf16_f32 v85, v86, v87
	v_cvt_pk_bf16_f32 v86, v80, v81
	v_lshl_add_u64 v[80:81], v[88:89], 0, s[12:13]
	s_mov_b64 s[30:31], -1
	s_and_b64 vcc, exec, s[2:3]
	v_cvt_pk_bf16_f32 v87, v82, v83
	s_cbranch_vccz .LBB0_2377
	global_store_dwordx4 v[80:81], v[84:87], off
	s_nop 1
	s_mov_b64 s[30:31], 0

.LBB0_2379:
	v_or_b32_e32 v80, 48, v142
	v_ashrrev_i32_e32 v81, 31, v80
	v_cvt_pk_bf16_f32 v76, v76, v77
	v_cvt_pk_bf16_f32 v77, v78, v79
	v_cvt_pk_bf16_f32 v78, v72, v73
	v_lshlrev_b64 v[72:73], 11, v[80:81]
	v_lshl_add_u64 v[72:73], s[6:7], 0, v[72:73]
	v_lshl_add_u64 v[72:73], v[140:141], 1, v[72:73]
	s_mov_b64 s[30:31], -1
	s_and_b64 vcc, exec, s[2:3]
	v_cvt_pk_bf16_f32 v79, v74, v75
	s_cbranch_vccz .LBB0_2381
	global_store_dwordx4 v[72:73], v[76:79], off
	s_nop 1
	s_mov_b64 s[30:31], 0

.LBB0_2383:
	v_cvt_pk_bf16_f32 v68, v68, v69
	v_cvt_pk_bf16_f32 v69, v70, v71
	v_cvt_pk_bf16_f32 v70, v64, v65
	v_lshl_add_u64 v[64:65], v[72:73], 0, s[12:13]
	s_mov_b64 s[30:31], -1
	s_and_b64 vcc, exec, s[2:3]
	v_cvt_pk_bf16_f32 v71, v66, v67
	s_cbranch_vccz .LBB0_2385
	global_store_dwordx4 v[64:65], v[68:71], off
	s_nop 1
	s_mov_b64 s[30:31], 0

.LBB0_2387:
	v_lshlrev_b64 v[64:65], 11, v[142:143]
	v_cvt_pk_bf16_f32 v60, v60, v61
	v_cvt_pk_bf16_f32 v61, v62, v63
	v_cvt_pk_bf16_f32 v62, v56, v57
	v_lshl_add_u64 v[56:57], s[6:7], 0, v[64:65]
	v_lshl_add_u64 v[56:57], v[140:141], 1, v[56:57]
	v_lshl_add_u64 v[56:57], v[56:57], 0, s[14:15]
	s_mov_b64 s[30:31], -1
	s_and_b64 vcc, exec, s[2:3]
	v_cvt_pk_bf16_f32 v63, v58, v59
	s_cbranch_vccz .LBB0_2389
	global_store_dwordx4 v[56:57], v[60:63], off
	s_nop 1
	s_mov_b64 s[30:31], 0

.LBB0_2391:
	v_cvt_pk_bf16_f32 v52, v52, v53
	v_cvt_pk_bf16_f32 v53, v54, v55
	v_cvt_pk_bf16_f32 v54, v48, v49
	v_lshl_add_u64 v[48:49], v[56:57], 0, s[12:13]
	s_mov_b64 s[30:31], -1
	s_and_b64 vcc, exec, s[2:3]
	v_cvt_pk_bf16_f32 v55, v50, v51
	s_cbranch_vccz .LBB0_2393
	global_store_dwordx4 v[48:49], v[52:55], off
	s_nop 1
	s_mov_b64 s[30:31], 0

.LBB0_2395:
	v_lshlrev_b64 v[48:49], 11, v[142:143]
	v_cvt_pk_bf16_f32 v44, v44, v45
	v_cvt_pk_bf16_f32 v45, v46, v47
	v_cvt_pk_bf16_f32 v46, v40, v41
	v_lshl_add_u64 v[40:41], s[6:7], 0, v[48:49]
	v_lshl_add_u64 v[40:41], v[140:141], 1, v[40:41]
	v_lshl_add_u64 v[40:41], v[40:41], 0, s[16:17]
	s_mov_b64 s[30:31], -1
	s_and_b64 vcc, exec, s[2:3]
	v_cvt_pk_bf16_f32 v47, v42, v43
	s_cbranch_vccz .LBB0_2397
	global_store_dwordx4 v[40:41], v[44:47], off
	s_nop 1
	s_mov_b64 s[30:31], 0

.LBB0_2399:
	v_cvt_pk_bf16_f32 v36, v36, v37
	v_cvt_pk_bf16_f32 v37, v38, v39
	v_cvt_pk_bf16_f32 v38, v32, v33
	v_lshl_add_u64 v[32:33], v[40:41], 0, s[12:13]
	s_mov_b64 s[30:31], -1
	s_and_b64 vcc, exec, s[2:3]
	v_cvt_pk_bf16_f32 v39, v34, v35
	s_cbranch_vccz .LBB0_2401
	global_store_dwordx4 v[32:33], v[36:39], off
	s_nop 1
	s_mov_b64 s[30:31], 0

.LBB0_2403:
	v_lshlrev_b64 v[32:33], 11, v[142:143]
	v_cvt_pk_bf16_f32 v28, v28, v29
	v_cvt_pk_bf16_f32 v29, v30, v31
	v_cvt_pk_bf16_f32 v30, v24, v25
	v_lshl_add_u64 v[24:25], s[6:7], 0, v[32:33]
	v_lshl_add_u64 v[24:25], v[140:141], 1, v[24:25]
	v_lshl_add_u64 v[24:25], v[24:25], 0, s[18:19]
	s_mov_b64 s[30:31], -1
	s_and_b64 vcc, exec, s[2:3]
	v_cvt_pk_bf16_f32 v31, v26, v27
	s_cbranch_vccz .LBB0_2405
	global_store_dwordx4 v[24:25], v[28:31], off
	s_nop 1
	s_mov_b64 s[30:31], 0

.LBB0_2407:
	v_cvt_pk_bf16_f32 v20, v20, v21
	v_cvt_pk_bf16_f32 v21, v22, v23
	v_cvt_pk_bf16_f32 v22, v16, v17
	v_lshl_add_u64 v[16:17], v[24:25], 0, s[12:13]
	s_mov_b64 s[30:31], -1
	s_and_b64 vcc, exec, s[2:3]
	v_cvt_pk_bf16_f32 v23, v18, v19
	s_cbranch_vccz .LBB0_2409
	global_store_dwordx4 v[16:17], v[20:23], off
	s_nop 1
	s_mov_b64 s[30:31], 0

.LBB0_2411:
	v_lshlrev_b64 v[16:17], 11, v[142:143]
	v_cvt_pk_bf16_f32 v12, v12, v13
	v_cvt_pk_bf16_f32 v13, v14, v15
	v_cvt_pk_bf16_f32 v14, v8, v9
	v_lshl_add_u64 v[8:9], s[6:7], 0, v[16:17]
	v_lshl_add_u64 v[8:9], v[140:141], 1, v[8:9]
	v_lshl_add_u64 v[8:9], v[8:9], 0, s[20:21]
	s_mov_b64 s[30:31], -1
	s_and_b64 vcc, exec, s[2:3]
	v_cvt_pk_bf16_f32 v15, v10, v11
	s_cbranch_vccz .LBB0_2413
	global_store_dwordx4 v[8:9], v[12:15], off
	s_nop 1
	s_mov_b64 s[30:31], 0

.LBB0_2415:
	v_cvt_pk_bf16_f32 v4, v4, v5
	v_cvt_pk_bf16_f32 v5, v6, v7
	v_cvt_pk_bf16_f32 v6, v0, v1
	v_lshl_add_u64 v[0:1], v[8:9], 0, s[12:13]
	s_mov_b64 s[30:31], -1
	s_and_b64 vcc, exec, s[2:3]
	v_cvt_pk_bf16_f32 v7, v2, v3
	s_cbranch_vccz .LBB0_2418
	global_store_dwordx4 v[0:1], v[4:7], off
	s_nop 1
	s_cbranch_execz .LBB0_2419
